# P6 loop: first V-fragment read group of PV issued before finishSM (LDS latency under softmax VALU)
# baseline (speedup 1.0000x reference)
; __device__ __forceinline__ void finishSM(f32x16& p0, f32x16& p1, float alpha, float& l_reg, bf16x8& pa0, bf16x8& pa1, bf16x8& pa2, bf16x8& pa3) {
; #pragma unroll
;     for (int r = 0; r < 16; ++r) p1[r] = __builtin_amdgcn_exp2f(p1[r]);
;     float ps = 0;
; #pragma unroll
;     for (int r = 0; r < 16; ++r) ps += p0[r];
; #pragma unroll
;     for (int r = 0; r < 16; ++r) ps += p1[r];
;     { auto rr = __builtin_amdgcn_permlane32_swap(__float_as_uint(ps), __float_as_uint(ps), false, false);
;       ps = __uint_as_float(rr[0]) + __uint_as_float(rr[1]); }
;     l_reg = l_reg * alpha + ps;
;     PK4(p0, 0, pa0); PK4(p0, 8, pa1); PK4(p1, 0, pa2); PK4(p1, 8, pa3);
; }
; template <int VB, bool SK>
; __device__ __forceinline__ void pv_tile(f32x16* o, int vb0, bf16x8 pa0, bf16x8 pa1, bf16x8 pa2, bf16x8 pa3, bool act) {
;     if (SK && !act) return;
;     ...
;     PV_D0(0); PV_D0(1); PV_D0(2); PV_D0(3);
.LBB0_1334:
	s_andn2_b64 s[6:7], exec, s[84:85]
	s_andn2_b64 vcc, exec, s[84:85]
	s_cbranch_vccnz .LBB0_1336
	ds_read_b64_tr_b16 v[144:145], v226 offset:0
	ds_read_b64_tr_b16 v[146:147], v226 offset:0x800
	ds_read_b64_tr_b16 v[148:149], v226 offset:0x1000
	ds_read_b64_tr_b16 v[150:151], v226 offset:0x1800
	ds_read_b64_tr_b16 v[152:153], v226 offset:0x2000
	ds_read_b64_tr_b16 v[154:155], v226 offset:0x2800
	ds_read_b64_tr_b16 v[156:157], v226 offset:0x3000
	ds_read_b64_tr_b16 v[158:159], v226 offset:0x3800
	v_add_f32_e32 v2, v128, v129
	v_add_f32_e32 v2, v130, v2
	v_add_f32_e32 v2, v131, v2
	v_add_f32_e32 v2, v132, v2
	v_add_f32_e32 v2, v133, v2
	v_add_f32_e32 v2, v134, v2
	v_add_f32_e32 v2, v135, v2
	v_add_f32_e32 v2, v136, v2
	v_add_f32_e32 v2, v137, v2
	v_add_f32_e32 v2, v138, v2
	v_add_f32_e32 v2, v139, v2
	v_exp_f32_e32 v96, v96
	v_add_f32_e32 v2, v140, v2
	v_exp_f32_e32 v97, v97
	v_add_f32_e32 v2, v141, v2
	v_exp_f32_e32 v98, v98
	v_add_f32_e32 v2, v142, v2
	v_exp_f32_e32 v99, v99
	v_add_f32_e32 v2, v143, v2
	v_exp_f32_e32 v100, v100
	v_add_f32_e32 v2, v96, v2
	v_exp_f32_e32 v101, v101
	v_add_f32_e32 v2, v97, v2
	v_exp_f32_e32 v102, v102
	v_add_f32_e32 v2, v98, v2
	v_exp_f32_e32 v103, v103
	v_add_f32_e32 v2, v99, v2
	v_exp_f32_e32 v104, v104
	v_add_f32_e32 v2, v100, v2
	v_exp_f32_e32 v105, v105
	v_add_f32_e32 v2, v101, v2
	v_exp_f32_e32 v106, v106
	v_add_f32_e32 v2, v102, v2
	v_exp_f32_e32 v107, v107
	v_add_f32_e32 v2, v103, v2
	v_exp_f32_e32 v108, v108
	v_add_f32_e32 v2, v104, v2
	v_exp_f32_e32 v109, v109
	v_add_f32_e32 v2, v105, v2
	v_exp_f32_e32 v110, v110
	v_add_f32_e32 v2, v106, v2
	v_exp_f32_e32 v111, v111
	v_add_f32_e32 v2, v107, v2
	v_add_f32_e32 v2, v108, v2
	v_add_f32_e32 v2, v109, v2
	v_add_f32_e32 v2, v110, v2
	v_add_f32_e32 v2, v111, v2
	v_mov_b32_e32 v3, v2
	s_nop 1
	v_permlane32_swap_b32_e32 v2, v3
	v_add_f32_e32 v2, v2, v3
	v_fma_f32 v227, v243, v227, v2
	v_cvt_pk_bf16_f32 v192, v128, v129
	v_cvt_pk_bf16_f32 v193, v130, v131
	v_cvt_pk_bf16_f32 v194, v132, v133
	v_cvt_pk_bf16_f32 v195, v134, v135
	v_cvt_pk_bf16_f32 v196, v136, v137
	v_cvt_pk_bf16_f32 v197, v138, v139
	v_cvt_pk_bf16_f32 v198, v140, v141
	v_cvt_pk_bf16_f32 v199, v142, v143
	v_cvt_pk_bf16_f32 v200, v96, v97
	v_cvt_pk_bf16_f32 v201, v98, v99
	v_cvt_pk_bf16_f32 v202, v100, v101
	v_cvt_pk_bf16_f32 v203, v102, v103
	v_cvt_pk_bf16_f32 v204, v104, v105
	v_cvt_pk_bf16_f32 v205, v106, v107
	v_cvt_pk_bf16_f32 v206, v108, v109
	v_cvt_pk_bf16_f32 v207, v110, v111
	s_nop 0
	v_permlane32_swap_b32_e32 v192, v194
	v_permlane32_swap_b32_e32 v193, v195
	v_permlane32_swap_b32_e32 v196, v198
	v_permlane32_swap_b32_e32 v197, v199
	v_permlane32_swap_b32_e32 v200, v202
	v_permlane32_swap_b32_e32 v201, v203
	v_permlane32_swap_b32_e32 v204, v206
	v_permlane32_swap_b32_e32 v205, v207
.LBB0_1336:
	s_mov_b32 s20, 0x1000000
	global_load_dwordx4 v[10:13], v248, s[98:99]
	global_load_dwordx4 v[208:211], v249, s[98:99]
	global_load_dwordx4 v[2:5], v248, s[100:101]
	global_load_dwordx4 v[6:9], v249, s[100:101]
	s_add_u32 s98, s98, 0x4000
	s_addc_u32 s99, s99, 0
	s_add_u32 s100, s100, 0x4000
	s_addc_u32 s101, s101, 0
	s_and_b64 vcc, exec, s[6:7]
	s_cbranch_vccnz .LBB0_1338
	s_waitcnt lgkmcnt(0)
	v_mfma_f32_32x32x16_bf16 v[64:79], v[192:195], v[144:147], v[64:79]
	ds_read_b64_tr_b16 v[144:145], v226 offset:0x200
	ds_read_b64_tr_b16 v[146:147], v226 offset:0xa00
	v_mfma_f32_32x32x16_bf16 v[64:79], v[196:199], v[148:151], v[64:79]
	ds_read_b64_tr_b16 v[148:149], v226 offset:0x1200
	ds_read_b64_tr_b16 v[150:151], v226 offset:0x1a00
	v_mfma_f32_32x32x16_bf16 v[64:79], v[200:203], v[152:155], v[64:79]
	ds_read_b64_tr_b16 v[152:153], v226 offset:0x2200
	ds_read_b64_tr_b16 v[154:155], v226 offset:0x2a00
	v_mfma_f32_32x32x16_bf16 v[64:79], v[204:207], v[156:159], v[64:79]
	ds_read_b64_tr_b16 v[156:157], v226 offset:0x3200
	ds_read_b64_tr_b16 v[158:159], v226 offset:0x3a00
	s_waitcnt lgkmcnt(0)
	v_mfma_f32_32x32x16_bf16 v[48:63], v[192:195], v[144:147], v[48:63]
	ds_read_b64_tr_b16 v[144:145], v226 offset:0x400
	ds_read_b64_tr_b16 v[146:147], v226 offset:0xc00
	v_mfma_f32_32x32x16_bf16 v[48:63], v[196:199], v[148:151], v[48:63]
	ds_read_b64_tr_b16 v[148:149], v226 offset:0x1400
	ds_read_b64_tr_b16 v[150:151], v226 offset:0x1c00
	v_mfma_f32_32x32x16_bf16 v[48:63], v[200:203], v[152:155], v[48:63]
	ds_read_b64_tr_b16 v[152:153], v226 offset:0x2400
	ds_read_b64_tr_b16 v[154:155], v226 offset:0x2c00
	v_mfma_f32_32x32x16_bf16 v[48:63], v[204:207], v[156:159], v[48:63]
	ds_read_b64_tr_b16 v[156:157], v226 offset:0x3400
	ds_read_b64_tr_b16 v[158:159], v226 offset:0x3c00
	s_waitcnt lgkmcnt(0)
	v_mfma_f32_32x32x16_bf16 v[32:47], v[192:195], v[144:147], v[32:47]
	ds_read_b64_tr_b16 v[144:145], v226 offset:0x600
	ds_read_b64_tr_b16 v[146:147], v226 offset:0xe00
	v_mfma_f32_32x32x16_bf16 v[32:47], v[196:199], v[148:151], v[32:47]
	ds_read_b64_tr_b16 v[148:149], v226 offset:0x1600
	ds_read_b64_tr_b16 v[150:151], v226 offset:0x1e00
	v_mfma_f32_32x32x16_bf16 v[32:47], v[200:203], v[152:155], v[32:47]
	ds_read_b64_tr_b16 v[152:153], v226 offset:0x2600
	ds_read_b64_tr_b16 v[154:155], v226 offset:0x2e00
	v_mfma_f32_32x32x16_bf16 v[32:47], v[204:207], v[156:159], v[32:47]
	ds_read_b64_tr_b16 v[156:157], v226 offset:0x3600
	ds_read_b64_tr_b16 v[158:159], v226 offset:0x3e00
	s_waitcnt lgkmcnt(0)
	v_mfma_f32_32x32x16_bf16 v[16:31], v[192:195], v[144:147], v[16:31]
	v_mfma_f32_32x32x16_bf16 v[16:31], v[196:199], v[148:151], v[16:31]
	v_mfma_f32_32x32x16_bf16 v[16:31], v[200:203], v[152:155], v[16:31]
	v_mfma_f32_32x32x16_bf16 v[16:31], v[204:207], v[156:159], v[16:31]

; __device__ __forceinline__ void finishSM(f32x16& p0, f32x16& p1, float alpha, float& l_reg, bf16x8& pa0, bf16x8& pa1, bf16x8& pa2, bf16x8& pa3) {
; #pragma unroll
;     for (int r = 0; r < 16; ++r) p1[r] = __builtin_amdgcn_exp2f(p1[r]);
;     float ps = 0;
; #pragma unroll
;     for (int r = 0; r < 16; ++r) ps += p0[r];
; #pragma unroll
;     for (int r = 0; r < 16; ++r) ps += p1[r];
;     { auto rr = __builtin_amdgcn_permlane32_swap(__float_as_uint(ps), __float_as_uint(ps), false, false);
;       ps = __uint_as_float(rr[0]) + __uint_as_float(rr[1]); }
;     l_reg = l_reg * alpha + ps;
;     PK4(p0, 0, pa0); PK4(p0, 8, pa1); PK4(p1, 0, pa2); PK4(p1, 8, pa3);
; }
.LBB0_1384:
	s_and_b64 vcc, exec, s[4:5]
	s_cbranch_vccnz .LBB0_1386
	ds_read_b64_tr_b16 v[144:145], v226 offset:0x4000
	ds_read_b64_tr_b16 v[146:147], v226 offset:0x4800
	ds_read_b64_tr_b16 v[148:149], v226 offset:0x5000
	ds_read_b64_tr_b16 v[150:151], v226 offset:0x5800
	ds_read_b64_tr_b16 v[152:153], v226 offset:0x6000
	ds_read_b64_tr_b16 v[154:155], v226 offset:0x6800
	ds_read_b64_tr_b16 v[156:157], v226 offset:0x7000
	ds_read_b64_tr_b16 v[158:159], v226 offset:0x7800
	v_add_f32_e32 v15, v112, v113
	v_add_f32_e32 v15, v114, v15
	v_add_f32_e32 v15, v115, v15
	v_add_f32_e32 v15, v116, v15
	v_add_f32_e32 v15, v117, v15
	v_add_f32_e32 v15, v118, v15
	v_add_f32_e32 v15, v119, v15
	v_add_f32_e32 v15, v120, v15
	v_add_f32_e32 v15, v121, v15
	v_add_f32_e32 v15, v122, v15
	v_add_f32_e32 v15, v123, v15
	v_exp_f32_e32 v80, v80
	v_add_f32_e32 v15, v124, v15
	v_exp_f32_e32 v81, v81
	v_add_f32_e32 v15, v125, v15
	v_exp_f32_e32 v82, v82
	v_add_f32_e32 v15, v126, v15
	v_exp_f32_e32 v83, v83
	v_add_f32_e32 v15, v127, v15
	v_exp_f32_e32 v84, v84
	v_add_f32_e32 v15, v80, v15
	v_exp_f32_e32 v85, v85
	v_add_f32_e32 v15, v81, v15
	v_exp_f32_e32 v86, v86
	v_add_f32_e32 v15, v82, v15
	v_exp_f32_e32 v87, v87
	v_add_f32_e32 v15, v83, v15
	v_exp_f32_e32 v88, v88
	v_add_f32_e32 v15, v84, v15
	v_exp_f32_e32 v89, v89
	v_add_f32_e32 v15, v85, v15
	v_exp_f32_e32 v90, v90
	v_add_f32_e32 v15, v86, v15
	v_exp_f32_e32 v91, v91
	v_add_f32_e32 v15, v87, v15
	v_exp_f32_e32 v92, v92
	v_add_f32_e32 v15, v88, v15
	v_exp_f32_e32 v93, v93
	v_add_f32_e32 v15, v89, v15
	v_exp_f32_e32 v94, v94
	v_add_f32_e32 v15, v90, v15
	v_exp_f32_e32 v95, v95
	v_add_f32_e32 v15, v91, v15
	v_add_f32_e32 v15, v92, v15
	v_add_f32_e32 v15, v93, v15
	v_add_f32_e32 v15, v94, v15
	v_add_f32_e32 v15, v95, v15
	v_mov_b32_e32 v2, v15
	s_nop 1
	v_permlane32_swap_b32_e32 v15, v2
	v_add_f32_e32 v15, v15, v2
	v_fma_f32 v227, v227, v14, v15
	v_cvt_pk_bf16_f32 v192, v112, v113
	v_cvt_pk_bf16_f32 v193, v114, v115
	v_cvt_pk_bf16_f32 v194, v116, v117
	v_cvt_pk_bf16_f32 v195, v118, v119
	v_cvt_pk_bf16_f32 v196, v120, v121
	v_cvt_pk_bf16_f32 v197, v122, v123
	v_cvt_pk_bf16_f32 v198, v124, v125
	v_cvt_pk_bf16_f32 v199, v126, v127
	v_cvt_pk_bf16_f32 v200, v80, v81
	v_cvt_pk_bf16_f32 v201, v82, v83
	v_cvt_pk_bf16_f32 v202, v84, v85
	v_cvt_pk_bf16_f32 v203, v86, v87
	v_cvt_pk_bf16_f32 v204, v88, v89
	v_cvt_pk_bf16_f32 v205, v90, v91
	v_cvt_pk_bf16_f32 v206, v92, v93
	v_cvt_pk_bf16_f32 v207, v94, v95
	s_nop 0
	v_permlane32_swap_b32_e32 v192, v194
	v_permlane32_swap_b32_e32 v193, v195
	v_permlane32_swap_b32_e32 v196, v198
	v_permlane32_swap_b32_e32 v197, v199
	v_permlane32_swap_b32_e32 v200, v202
	v_permlane32_swap_b32_e32 v201, v203
	v_permlane32_swap_b32_e32 v204, v206
	v_permlane32_swap_b32_e32 v205, v207

; template <int VB, bool SK>
; __device__ __forceinline__ void pv_tile(f32x16* o, int vb0, bf16x8 pa0, bf16x8 pa1, bf16x8 pa2, bf16x8 pa3, bool act) {
;     if (SK && !act) return;
;     ...
;     PV_D0(0); PV_D0(1); PV_D0(2); PV_D0(3);
.LBB0_1390:
	s_waitcnt lgkmcnt(0)
	s_nop 0
	v_mfma_f32_32x32x16_bf16 v[64:79], v[192:195], v[144:147], v[64:79]
	ds_read_b64_tr_b16 v[144:145], v226 offset:0x4200
	ds_read_b64_tr_b16 v[146:147], v226 offset:0x4a00
	v_mfma_f32_32x32x16_bf16 v[64:79], v[196:199], v[148:151], v[64:79]
	ds_read_b64_tr_b16 v[148:149], v226 offset:0x5200
	ds_read_b64_tr_b16 v[150:151], v226 offset:0x5a00
	v_mfma_f32_32x32x16_bf16 v[64:79], v[200:203], v[152:155], v[64:79]
	ds_read_b64_tr_b16 v[152:153], v226 offset:0x6200
	ds_read_b64_tr_b16 v[154:155], v226 offset:0x6a00
	v_mfma_f32_32x32x16_bf16 v[64:79], v[204:207], v[156:159], v[64:79]
	ds_read_b64_tr_b16 v[156:157], v226 offset:0x7200
	ds_read_b64_tr_b16 v[158:159], v226 offset:0x7a00
	s_waitcnt lgkmcnt(0)
	v_mfma_f32_32x32x16_bf16 v[48:63], v[192:195], v[144:147], v[48:63]
	ds_read_b64_tr_b16 v[144:145], v226 offset:0x4400
	ds_read_b64_tr_b16 v[146:147], v226 offset:0x4c00
	v_mfma_f32_32x32x16_bf16 v[48:63], v[196:199], v[148:151], v[48:63]
	ds_read_b64_tr_b16 v[148:149], v226 offset:0x5400
	ds_read_b64_tr_b16 v[150:151], v226 offset:0x5c00
	v_mfma_f32_32x32x16_bf16 v[48:63], v[200:203], v[152:155], v[48:63]
	ds_read_b64_tr_b16 v[152:153], v226 offset:0x6400
	ds_read_b64_tr_b16 v[154:155], v226 offset:0x6c00
	v_mfma_f32_32x32x16_bf16 v[48:63], v[204:207], v[156:159], v[48:63]
	ds_read_b64_tr_b16 v[156:157], v226 offset:0x7400
	ds_read_b64_tr_b16 v[158:159], v226 offset:0x7c00
	s_waitcnt lgkmcnt(0)
	v_mfma_f32_32x32x16_bf16 v[32:47], v[192:195], v[144:147], v[32:47]
	ds_read_b64_tr_b16 v[144:145], v226 offset:0x4600
	ds_read_b64_tr_b16 v[146:147], v226 offset:0x4e00
	v_mfma_f32_32x32x16_bf16 v[32:47], v[196:199], v[148:151], v[32:47]
	ds_read_b64_tr_b16 v[148:149], v226 offset:0x5600
	ds_read_b64_tr_b16 v[150:151], v226 offset:0x5e00
	v_mfma_f32_32x32x16_bf16 v[32:47], v[200:203], v[152:155], v[32:47]
	ds_read_b64_tr_b16 v[152:153], v226 offset:0x6600
	ds_read_b64_tr_b16 v[154:155], v226 offset:0x6e00
	v_mfma_f32_32x32x16_bf16 v[32:47], v[204:207], v[156:159], v[32:47]
	ds_read_b64_tr_b16 v[156:157], v226 offset:0x7600
	ds_read_b64_tr_b16 v[158:159], v226 offset:0x7e00
	s_waitcnt lgkmcnt(0)
	v_mfma_f32_32x32x16_bf16 v[16:31], v[192:195], v[144:147], v[16:31]
	v_mfma_f32_32x32x16_bf16 v[16:31], v[196:199], v[148:151], v[16:31]
	v_mfma_f32_32x32x16_bf16 v[16:31], v[200:203], v[152:155], v[16:31]
	v_mfma_f32_32x32x16_bf16 v[16:31], v[204:207], v[156:159], v[16:31]
	s_and_b64 vcc, exec, s[6:7]
	v_mov_b32_e32 v243, 1.0
	s_cbranch_vccnz .LBB0_1426
